# NORMKV row pass: 24 per-row parameter loads hoisted and batched (one wait), forget-gate 16-head dot products restructured with transpose-reduce (permlane32 swap + swizzle + DPP) instead of 16 serial w
# speedup vs baseline: 1.0210x; 1.0133x over previous
.LBB0_696:
	s_ashr_i32 s2, s50, 13
	s_ashr_i32 s3, s2, 31
	v_mad_i64_i32 v[80:81], s[0:1], s2, v252, v[8:9]
	v_mad_i64_i32 v[82:83], s[0:1], s2, v252, v[2:3]
	s_lshl_b64 s[0:1], s[2:3], 13
	v_lshl_add_u64 v[84:85], v[4:5], 0, s[0:1]
	v_lshl_add_u64 v[86:87], v[10:11], 0, s[0:1]
	global_load_dwordx4 v[100:103], v[6:7], off
	global_load_dwordx4 v[104:107], v[80:81], off
	global_load_dwordx4 v[108:111], v[82:83], off
	global_load_dwordx4 v[112:115], v[6:7], off offset:1024
	global_load_dwordx4 v[116:119], v[80:81], off offset:1024
	global_load_dwordx4 v[120:123], v[82:83], off offset:1024
	global_load_dwordx4 v[124:127], v[6:7], off offset:2048
	global_load_dwordx4 v[128:131], v[80:81], off offset:2048
	global_load_dwordx4 v[132:135], v[82:83], off offset:2048
	global_load_dwordx4 v[136:139], v[6:7], off offset:3072
	global_load_dwordx4 v[140:143], v[80:81], off offset:3072
	global_load_dwordx4 v[144:147], v[82:83], off offset:3072
	global_load_dwordx4 v[148:151], v[12:13], off
	global_load_dwordx4 v[152:155], v[86:87], off
	global_load_dwordx4 v[156:159], v[84:85], off
	global_load_dwordx4 v[160:163], v[12:13], off offset:1024
	global_load_dwordx4 v[164:167], v[86:87], off offset:1024
	global_load_dwordx4 v[168:171], v[84:85], off offset:1024
	global_load_dwordx4 v[172:175], v[12:13], off offset:2048
	global_load_dwordx4 v[176:179], v[86:87], off offset:2048
	global_load_dwordx4 v[180:183], v[84:85], off offset:2048
	global_load_dwordx4 v[184:187], v[12:13], off offset:3072
	global_load_dwordx4 v[188:191], v[86:87], off offset:3072
	global_load_dwordx4 v[192:195], v[84:85], off offset:3072
	v_cvt_f32_f16_sdwa v43, v32 dst_sel:DWORD dst_unused:UNUSED_PAD src0_sel:WORD_1
	v_cvt_f32_f16_e32 v42, v32
	v_cvt_f32_f16_sdwa v41, v33 dst_sel:DWORD dst_unused:UNUSED_PAD src0_sel:WORD_1
	v_cvt_f32_f16_e32 v40, v33
	v_cvt_f32_f16_sdwa v45, v30 dst_sel:DWORD dst_unused:UNUSED_PAD src0_sel:WORD_1
	v_cvt_f32_f16_e32 v44, v30
	v_cvt_f32_f16_sdwa v47, v31 dst_sel:DWORD dst_unused:UNUSED_PAD src0_sel:WORD_1
	v_cvt_f32_f16_e32 v46, v31
	v_cvt_f32_f16_sdwa v37, v26 dst_sel:DWORD dst_unused:UNUSED_PAD src0_sel:WORD_1
	v_cvt_f32_f16_e32 v36, v26
	v_pk_mul_f32 v[32:33], v[42:43], v[42:43]
	v_pk_mul_f32 v[34:35], v[40:41], v[40:41]
	v_pk_mul_f32 v[48:49], v[44:45], v[44:45]
	v_pk_mul_f32 v[50:51], v[46:47], v[46:47]
	v_pk_mul_f32 v[52:53], v[36:37], v[36:37]
	v_add_f32_e32 v50, v50, v51
	v_add_f32_e32 v48, v48, v49
	v_add_f32_e32 v34, v34, v35
	v_add_f32_e32 v32, v32, v33
	v_add_f32_e32 v48, v48, v50
	v_add_f32_e32 v32, v32, v34
	v_add_f32_e32 v34, v52, v53
	v_cvt_f32_f16_sdwa v39, v27 dst_sel:DWORD dst_unused:UNUSED_PAD src0_sel:WORD_1
	v_cvt_f32_f16_e32 v38, v27
	v_cvt_f32_f16_sdwa v27, v28 dst_sel:DWORD dst_unused:UNUSED_PAD src0_sel:WORD_1
	v_cvt_f32_f16_e32 v26, v28
	v_cvt_f32_f16_sdwa v31, v29 dst_sel:DWORD dst_unused:UNUSED_PAD src0_sel:WORD_1
	v_cvt_f32_f16_e32 v30, v29
	v_pk_mul_f32 v[54:55], v[38:39], v[38:39]
	v_pk_mul_f32 v[28:29], v[26:27], v[26:27]
	v_add_f32_e32 v33, v54, v55
	v_pk_mul_f32 v[58:59], v[30:31], v[30:31]
	v_add_f32_e32 v32, v32, v48
	v_add_f32_e32 v33, v34, v33
	v_add_f32_e32 v32, v33, v32
	v_add_f32_e32 v33, v58, v59
	v_add_f32_e32 v28, v28, v29
	v_add_f32_e32 v28, v28, v33
	v_add_f32_e32 v28, v28, v32
	ds_swizzle_b32 v29, v28 offset:swizzle(SWAP,1)
	s_ashr_i32 s2, s50, 13
	v_mad_i64_i32 v[48:49], s[0:1], s2, v252, v[8:9]
	v_lshl_add_u64 v[34:35], s[52:53], 0, v[0:1]
	s_waitcnt lgkmcnt(0)
	v_add_f32_e32 v28, v28, v29
	ds_swizzle_b32 v29, v28 offset:swizzle(SWAP,2)
	s_ashr_i32 s3, s2, 31
	s_waitcnt lgkmcnt(0)
	v_add_f32_e32 v28, v28, v29
	ds_swizzle_b32 v29, v28 offset:swizzle(SWAP,4)
	s_waitcnt lgkmcnt(0)
	v_add_f32_e32 v28, v28, v29
	ds_swizzle_b32 v29, v28 offset:swizzle(SWAP,8)
	s_waitcnt lgkmcnt(0)
	v_add_f32_e32 v28, v28, v29
	ds_swizzle_b32 v29, v28 offset:swizzle(SWAP,16)
	s_waitcnt lgkmcnt(0)
	v_add_f32_e32 v28, v28, v29
	v_mov_b32_e32 v29, v28
	s_nop 1
	v_permlane32_swap_b32_e32 v28, v29
	v_add_f32_e32 v28, v28, v29
	v_fmamk_f32 v28, v28, 0x3a800000, v244
	v_rsq_f32_e32 v32, v28
	v_mad_i64_i32 v[28:29], s[0:1], s2, v252, v[2:3]
	s_mov_b32 s0, 0x1b400000
	v_pk_mul_f32 v[40:41], v[40:41], v[32:33] op_sel_hi:[1,0]
	v_pk_mul_f32 v[42:43], v[42:43], v[32:33] op_sel_hi:[1,0]
	v_pk_mul_f32 v[46:47], v[46:47], v[32:33] op_sel_hi:[1,0]
	v_pk_mul_f32 v[44:45], v[44:45], v[32:33] op_sel_hi:[1,0]
	v_pk_mul_f32 v[38:39], v[38:39], v[32:33] op_sel_hi:[1,0]
	v_pk_mul_f32 v[36:37], v[36:37], v[32:33] op_sel_hi:[1,0]
	s_waitcnt vmcnt(0)
	v_mov_b64_e32 v[50:51], v[100:101]
	v_mov_b64_e32 v[52:53], v[102:103]
	v_pk_mul_f32 v[54:55], v[50:51], v[42:43]
	v_pk_mul_f32 v[58:59], v[52:53], v[40:41]
	v_mov_b64_e32 v[50:51], v[104:105]
	v_mov_b64_e32 v[52:53], v[106:107]
	v_pk_add_f32 v[60:61], v[52:53], 1.0 op_sel_hi:[1,0]
	v_pk_add_f32 v[62:63], v[50:51], 1.0 op_sel_hi:[1,0]
	v_mov_b64_e32 v[50:51], v[108:109]
	v_mov_b64_e32 v[52:53], v[110:111]
	v_pk_fma_f32 v[50:51], v[62:63], v[54:55], v[50:51]
	v_add_co_u32_e32 v54, vcc, s0, v34
	v_pk_fma_f32 v[52:53], v[60:61], v[58:59], v[52:53]
	s_nop 0
	v_addc_co_u32_e32 v55, vcc, 0, v35, vcc
	v_cvt_pk_bf16_f32 v50, v50, v51
	v_cvt_pk_bf16_f32 v51, v52, v53
	global_store_dwordx2 v[54:55], v[50:51], off
	v_mov_b64_e32 v[50:51], v[112:113]
	v_mov_b64_e32 v[52:53], v[114:115]
	s_lshl_b64 s[0:1], s[2:3], 13
	v_pk_mul_f32 v[58:59], v[50:51], v[44:45]
	v_pk_mul_f32 v[60:61], v[52:53], v[46:47]
	v_mov_b64_e32 v[50:51], v[116:117]
	v_mov_b64_e32 v[52:53], v[118:119]
	v_pk_add_f32 v[62:63], v[52:53], 1.0 op_sel_hi:[1,0]
	v_pk_add_f32 v[64:65], v[50:51], 1.0 op_sel_hi:[1,0]
	v_mov_b64_e32 v[50:51], v[120:121]
	v_mov_b64_e32 v[52:53], v[122:123]
	v_pk_fma_f32 v[50:51], v[64:65], v[58:59], v[50:51]
	v_pk_fma_f32 v[52:53], v[62:63], v[60:61], v[52:53]
	v_cvt_pk_bf16_f32 v50, v50, v51
	s_nop 0
	v_cvt_pk_bf16_f32 v51, v52, v53
	global_store_dwordx2 v[54:55], v[50:51], off offset:512
	v_mov_b64_e32 v[50:51], v[124:125]
	v_mov_b64_e32 v[52:53], v[126:127]
	v_pk_mul_f32 v[58:59], v[36:37], v[50:51]
	v_pk_mul_f32 v[60:61], v[38:39], v[52:53]
	v_mov_b64_e32 v[50:51], v[128:129]
	v_mov_b64_e32 v[52:53], v[130:131]
	v_pk_add_f32 v[62:63], v[52:53], 1.0 op_sel_hi:[1,0]
	v_pk_add_f32 v[64:65], v[50:51], 1.0 op_sel_hi:[1,0]
	v_mov_b64_e32 v[50:51], v[132:133]
	v_mov_b64_e32 v[52:53], v[134:135]
	v_pk_fma_f32 v[50:51], v[58:59], v[64:65], v[50:51]
	v_pk_fma_f32 v[52:53], v[60:61], v[62:63], v[52:53]
	v_cvt_pk_bf16_f32 v50, v50, v51
	s_nop 0
	v_cvt_pk_bf16_f32 v51, v52, v53
	global_store_dwordx2 v[54:55], v[50:51], off offset:1024
	v_pk_mul_f32 v[50:51], v[30:31], v[32:33] op_sel_hi:[1,0]
	v_pk_mul_f32 v[52:53], v[26:27], v[32:33] op_sel_hi:[1,0]
	v_mov_b64_e32 v[30:31], v[136:137]
	v_mov_b64_e32 v[32:33], v[138:139]
	v_pk_mul_f32 v[58:59], v[52:53], v[30:31]
	v_pk_mul_f32 v[60:61], v[50:51], v[32:33]
	v_mov_b64_e32 v[30:31], v[140:141]
	v_mov_b64_e32 v[32:33], v[142:143]
	s_nop 0
	v_mov_b64_e32 v[26:27], v[144:145]
	v_mov_b64_e32 v[28:29], v[146:147]
	v_lshl_add_u64 v[48:49], v[4:5], 0, s[0:1]
	v_pk_add_f32 v[30:31], v[30:31], 1.0 op_sel_hi:[1,0]
	v_pk_add_f32 v[32:33], v[32:33], 1.0 op_sel_hi:[1,0]
	v_pk_fma_f32 v[26:27], v[58:59], v[30:31], v[26:27]
	v_pk_fma_f32 v[28:29], v[60:61], v[32:33], v[28:29]
	v_cvt_pk_bf16_f32 v26, v26, v27
	s_nop 0
	v_cvt_pk_bf16_f32 v27, v28, v29
	global_store_dwordx2 v[54:55], v[26:27], off offset:1536
	v_mov_b64_e32 v[26:27], v[148:149]
	v_mov_b64_e32 v[28:29], v[150:151]
	v_lshl_add_u64 v[54:55], v[10:11], 0, s[0:1]
	s_mov_b32 s0, 0x3400000
	v_pk_mul_f32 v[32:33], v[42:43], v[26:27]
	v_pk_mul_f32 v[40:41], v[40:41], v[28:29]
	v_mov_b64_e32 v[26:27], v[152:153]
	v_mov_b64_e32 v[28:29], v[154:155]
	v_pk_add_f32 v[42:43], v[28:29], 1.0 op_sel_hi:[1,0]
	v_mov_b64_e32 v[28:29], v[156:157]
	v_mov_b64_e32 v[30:31], v[158:159]
	v_pk_add_f32 v[58:59], v[26:27], 1.0 op_sel_hi:[1,0]
	v_pk_fma_f32 v[26:27], v[40:41], v[42:43], v[30:31]
	v_pk_fma_f32 v[28:29], v[32:33], v[58:59], v[28:29]
	v_add_co_u32_e32 v58, vcc, s0, v34
	v_cvt_pk_bf16_f32 v30, v28, v29
	v_cvt_pk_bf16_f32 v31, v26, v27
	s_nop 1
	v_addc_co_u32_e32 v59, vcc, 0, v35, vcc
	global_store_dwordx2 v[58:59], v[30:31], off
	v_mov_b64_e32 v[30:31], v[160:161]
	v_mov_b64_e32 v[32:33], v[162:163]
	v_pk_mul_f32 v[40:41], v[44:45], v[30:31]
	v_pk_mul_f32 v[42:43], v[46:47], v[32:33]
	v_mov_b64_e32 v[30:31], v[164:165]
	v_mov_b64_e32 v[32:33], v[166:167]
	v_pk_add_f32 v[44:45], v[32:33], 1.0 op_sel_hi:[1,0]
	v_mov_b64_e32 v[32:33], v[168:169]
	v_mov_b64_e32 v[34:35], v[170:171]
	v_pk_add_f32 v[46:47], v[30:31], 1.0 op_sel_hi:[1,0]
	v_pk_fma_f32 v[30:31], v[42:43], v[44:45], v[34:35]
	v_pk_fma_f32 v[32:33], v[40:41], v[46:47], v[32:33]
	s_nop 0
	v_cvt_pk_bf16_f32 v34, v32, v33
	v_cvt_pk_bf16_f32 v35, v30, v31
	global_store_dwordx2 v[58:59], v[34:35], off offset:512
	v_mov_b64_e32 v[40:41], v[172:173]
	v_mov_b64_e32 v[42:43], v[174:175]
	v_pk_mul_f32 v[40:41], v[36:37], v[40:41]
	v_mov_b64_e32 v[34:35], v[176:177]
	v_mov_b64_e32 v[36:37], v[178:179]
	v_pk_mul_f32 v[38:39], v[38:39], v[42:43]
	v_pk_add_f32 v[42:43], v[36:37], 1.0 op_sel_hi:[1,0]
	v_pk_add_f32 v[44:45], v[34:35], 1.0 op_sel_hi:[1,0]
	v_mov_b64_e32 v[34:35], v[180:181]
	v_mov_b64_e32 v[36:37], v[182:183]
	v_pk_fma_f32 v[38:39], v[38:39], v[42:43], v[36:37]
	v_pk_fma_f32 v[40:41], v[40:41], v[44:45], v[34:35]
	s_nop 0
	v_cvt_pk_bf16_f32 v34, v40, v41
	v_cvt_pk_bf16_f32 v35, v38, v39
	global_store_dwordx2 v[58:59], v[34:35], off offset:1024
	v_mov_b64_e32 v[34:35], v[184:185]
	v_mov_b64_e32 v[36:37], v[186:187]
	v_pk_mul_f32 v[46:47], v[52:53], v[34:35]
	v_pk_mul_f32 v[50:51], v[50:51], v[36:37]
	v_mov_b64_e32 v[34:35], v[188:189]
	v_mov_b64_e32 v[36:37], v[190:191]
	v_mov_b64_e32 v[42:43], v[192:193]
	v_mov_b64_e32 v[44:45], v[194:195]
	v_pk_add_f32 v[36:37], v[36:37], 1.0 op_sel_hi:[1,0]
	v_pk_add_f32 v[52:53], v[34:35], 1.0 op_sel_hi:[1,0]
	v_pk_fma_f32 v[34:35], v[50:51], v[36:37], v[44:45]
	v_pk_fma_f32 v[36:37], v[46:47], v[52:53], v[42:43]
	s_nop 0
	v_cvt_pk_bf16_f32 v42, v36, v37
	v_cvt_pk_bf16_f32 v43, v34, v35
	global_store_dwordx2 v[58:59], v[42:43], off offset:1536
	v_mbcnt_lo_u32_b32 v96, -1, 0
	v_mbcnt_hi_u32_b32 v96, -1, v96
	ds_read_b128 v[100:103], v56
	ds_read_b128 v[104:107], v56 offset:1024
	ds_read_b128 v[108:111], v56 offset:2048
	ds_read_b128 v[112:115], v56 offset:3072
	ds_read_b128 v[116:119], v56 offset:4096
	ds_read_b128 v[120:123], v56 offset:5120
	ds_read_b128 v[124:127], v56 offset:6144
	ds_read_b128 v[128:131], v56 offset:7168
	ds_read_b128 v[132:135], v56 offset:8192
	ds_read_b128 v[136:139], v56 offset:9216
	ds_read_b128 v[140:143], v56 offset:10240
	ds_read_b128 v[144:147], v56 offset:11264
	v_lshrrev_b32_e32 v97, 2, v96
	v_and_b32_e32 v98, 3, v96
	v_lshl_or_b32 v97, v97, 4, v98
	v_and_b32_e32 v97, 63, v97
	v_lshlrev_b32_e32 v97, 2, v97
	s_waitcnt lgkmcnt(8)
	v_mul_f32_e32 v228, v29, v101
	v_mul_f32_e32 v229, v27, v103
	v_mul_f32_e32 v230, v33, v105
	v_mul_f32_e32 v231, v31, v107
	v_mul_f32_e32 v232, v41, v109
	v_mul_f32_e32 v233, v39, v111
	v_mul_f32_e32 v234, v37, v113
	v_mul_f32_e32 v235, v35, v115
	v_fmac_f32_e32 v228, v28, v100
	v_fmac_f32_e32 v229, v26, v102
	v_fmac_f32_e32 v230, v32, v104
	v_fmac_f32_e32 v231, v30, v106
	v_fmac_f32_e32 v232, v40, v108
	v_fmac_f32_e32 v233, v38, v110
	v_fmac_f32_e32 v234, v36, v112
	v_fmac_f32_e32 v235, v34, v114
	v_add_f32_e32 v228, v228, v229
	v_add_f32_e32 v230, v230, v231
	v_add_f32_e32 v232, v232, v233
	v_add_f32_e32 v234, v234, v235
	v_add_f32_e32 v80, 0, v228
	v_add_f32_e32 v80, v80, v230
	v_add_f32_e32 v80, v80, v232
	v_add_f32_e32 v80, v80, v234
	ds_read_b128 v[100:103], v56 offset:12288
	ds_read_b128 v[104:107], v56 offset:13312
	ds_read_b128 v[108:111], v56 offset:14336
	ds_read_b128 v[112:115], v56 offset:15360
	s_waitcnt lgkmcnt(8)
	v_mul_f32_e32 v228, v29, v117
	v_mul_f32_e32 v229, v27, v119
	v_mul_f32_e32 v230, v33, v121
	v_mul_f32_e32 v231, v31, v123
	v_mul_f32_e32 v232, v41, v125
	v_mul_f32_e32 v233, v39, v127
	v_mul_f32_e32 v234, v37, v129
	v_mul_f32_e32 v235, v35, v131
	v_fmac_f32_e32 v228, v28, v116
	v_fmac_f32_e32 v229, v26, v118
	v_fmac_f32_e32 v230, v32, v120
	v_fmac_f32_e32 v231, v30, v122
	v_fmac_f32_e32 v232, v40, v124
	v_fmac_f32_e32 v233, v38, v126
	v_fmac_f32_e32 v234, v36, v128
	v_fmac_f32_e32 v235, v34, v130
	v_add_f32_e32 v228, v228, v229
	v_add_f32_e32 v230, v230, v231
	v_add_f32_e32 v232, v232, v233
	v_add_f32_e32 v234, v234, v235
	v_add_f32_e32 v81, 0, v228
	v_add_f32_e32 v81, v81, v230
	v_add_f32_e32 v81, v81, v232
	v_add_f32_e32 v81, v81, v234
	ds_read_b128 v[116:119], v56 offset:16384
	ds_read_b128 v[120:123], v56 offset:17408
	ds_read_b128 v[124:127], v56 offset:18432
	ds_read_b128 v[128:131], v56 offset:19456
	s_waitcnt lgkmcnt(8)
	v_mul_f32_e32 v228, v29, v133
	v_mul_f32_e32 v229, v27, v135
	v_mul_f32_e32 v230, v33, v137
	v_mul_f32_e32 v231, v31, v139
	v_mul_f32_e32 v232, v41, v141
	v_mul_f32_e32 v233, v39, v143
	v_mul_f32_e32 v234, v37, v145
	v_mul_f32_e32 v235, v35, v147
	v_fmac_f32_e32 v228, v28, v132
	v_fmac_f32_e32 v229, v26, v134
	v_fmac_f32_e32 v230, v32, v136
	v_fmac_f32_e32 v231, v30, v138
	v_fmac_f32_e32 v232, v40, v140
	v_fmac_f32_e32 v233, v38, v142
	v_fmac_f32_e32 v234, v36, v144
	v_fmac_f32_e32 v235, v34, v146
	v_add_f32_e32 v228, v228, v229
	v_add_f32_e32 v230, v230, v231
	v_add_f32_e32 v232, v232, v233
	v_add_f32_e32 v234, v234, v235
	v_add_f32_e32 v82, 0, v228
	v_add_f32_e32 v82, v82, v230
	v_add_f32_e32 v82, v82, v232
	v_add_f32_e32 v82, v82, v234
	ds_read_b128 v[132:135], v56 offset:20480
	ds_read_b128 v[136:139], v56 offset:21504
	ds_read_b128 v[140:143], v56 offset:22528
	ds_read_b128 v[144:147], v56 offset:23552
	s_waitcnt lgkmcnt(8)
	v_mul_f32_e32 v228, v29, v101
	v_mul_f32_e32 v229, v27, v103
	v_mul_f32_e32 v230, v33, v105
	v_mul_f32_e32 v231, v31, v107
	v_mul_f32_e32 v232, v41, v109
	v_mul_f32_e32 v233, v39, v111
	v_mul_f32_e32 v234, v37, v113
	v_mul_f32_e32 v235, v35, v115
	v_fmac_f32_e32 v228, v28, v100
	v_fmac_f32_e32 v229, v26, v102
	v_fmac_f32_e32 v230, v32, v104
	v_fmac_f32_e32 v231, v30, v106
	v_fmac_f32_e32 v232, v40, v108
	v_fmac_f32_e32 v233, v38, v110
	v_fmac_f32_e32 v234, v36, v112
	v_fmac_f32_e32 v235, v34, v114
	v_add_f32_e32 v228, v228, v229
	v_add_f32_e32 v230, v230, v231
	v_add_f32_e32 v232, v232, v233
	v_add_f32_e32 v234, v234, v235
	v_add_f32_e32 v83, 0, v228
	v_add_f32_e32 v83, v83, v230
	v_add_f32_e32 v83, v83, v232
	v_add_f32_e32 v83, v83, v234
	ds_read_b128 v[100:103], v56 offset:24576
	ds_read_b128 v[104:107], v56 offset:25600
	ds_read_b128 v[108:111], v56 offset:26624
	ds_read_b128 v[112:115], v56 offset:27648
	s_waitcnt lgkmcnt(8)
	v_mul_f32_e32 v228, v29, v117
	v_mul_f32_e32 v229, v27, v119
	v_mul_f32_e32 v230, v33, v121
	v_mul_f32_e32 v231, v31, v123
	v_mul_f32_e32 v232, v41, v125
	v_mul_f32_e32 v233, v39, v127
	v_mul_f32_e32 v234, v37, v129
	v_mul_f32_e32 v235, v35, v131
	v_fmac_f32_e32 v228, v28, v116
	v_fmac_f32_e32 v229, v26, v118
	v_fmac_f32_e32 v230, v32, v120
	v_fmac_f32_e32 v231, v30, v122
	v_fmac_f32_e32 v232, v40, v124
	v_fmac_f32_e32 v233, v38, v126
	v_fmac_f32_e32 v234, v36, v128
	v_fmac_f32_e32 v235, v34, v130
	v_add_f32_e32 v228, v228, v229
	v_add_f32_e32 v230, v230, v231
	v_add_f32_e32 v232, v232, v233
	v_add_f32_e32 v234, v234, v235
	v_add_f32_e32 v84, 0, v228
	v_add_f32_e32 v84, v84, v230
	v_add_f32_e32 v84, v84, v232
	v_add_f32_e32 v84, v84, v234
	ds_read_b128 v[116:119], v56 offset:28672
	ds_read_b128 v[120:123], v56 offset:29696
	ds_read_b128 v[124:127], v56 offset:30720
	ds_read_b128 v[128:131], v56 offset:31744
	s_waitcnt lgkmcnt(8)
	v_mul_f32_e32 v228, v29, v133
	v_mul_f32_e32 v229, v27, v135
	v_mul_f32_e32 v230, v33, v137
	v_mul_f32_e32 v231, v31, v139
	v_mul_f32_e32 v232, v41, v141
	v_mul_f32_e32 v233, v39, v143
	v_mul_f32_e32 v234, v37, v145
	v_mul_f32_e32 v235, v35, v147
	v_fmac_f32_e32 v228, v28, v132
	v_fmac_f32_e32 v229, v26, v134
	v_fmac_f32_e32 v230, v32, v136
	v_fmac_f32_e32 v231, v30, v138
	v_fmac_f32_e32 v232, v40, v140
	v_fmac_f32_e32 v233, v38, v142
	v_fmac_f32_e32 v234, v36, v144
	v_fmac_f32_e32 v235, v34, v146
	v_add_f32_e32 v228, v228, v229
	v_add_f32_e32 v230, v230, v231
	v_add_f32_e32 v232, v232, v233
	v_add_f32_e32 v234, v234, v235
	v_add_f32_e32 v85, 0, v228
	v_add_f32_e32 v85, v85, v230
	v_add_f32_e32 v85, v85, v232
	v_add_f32_e32 v85, v85, v234
	ds_read_b128 v[132:135], v56 offset:32768
	ds_read_b128 v[136:139], v56 offset:33792
	ds_read_b128 v[140:143], v56 offset:34816
	ds_read_b128 v[144:147], v56 offset:35840
	s_waitcnt lgkmcnt(8)
	v_mul_f32_e32 v228, v29, v101
	v_mul_f32_e32 v229, v27, v103
	v_mul_f32_e32 v230, v33, v105
	v_mul_f32_e32 v231, v31, v107
	v_mul_f32_e32 v232, v41, v109
	v_mul_f32_e32 v233, v39, v111
	v_mul_f32_e32 v234, v37, v113
	v_mul_f32_e32 v235, v35, v115
	v_fmac_f32_e32 v228, v28, v100
	v_fmac_f32_e32 v229, v26, v102
	v_fmac_f32_e32 v230, v32, v104
	v_fmac_f32_e32 v231, v30, v106
	v_fmac_f32_e32 v232, v40, v108
	v_fmac_f32_e32 v233, v38, v110
	v_fmac_f32_e32 v234, v36, v112
	v_fmac_f32_e32 v235, v34, v114
	v_add_f32_e32 v228, v228, v229
	v_add_f32_e32 v230, v230, v231
	v_add_f32_e32 v232, v232, v233
	v_add_f32_e32 v234, v234, v235
	v_add_f32_e32 v86, 0, v228
	v_add_f32_e32 v86, v86, v230
	v_add_f32_e32 v86, v86, v232
	v_add_f32_e32 v86, v86, v234
	ds_read_b128 v[100:103], v56 offset:36864
	ds_read_b128 v[104:107], v56 offset:37888
	ds_read_b128 v[108:111], v56 offset:38912
	ds_read_b128 v[112:115], v56 offset:39936
	s_waitcnt lgkmcnt(8)
	v_mul_f32_e32 v228, v29, v117
	v_mul_f32_e32 v229, v27, v119
	v_mul_f32_e32 v230, v33, v121
	v_mul_f32_e32 v231, v31, v123
	v_mul_f32_e32 v232, v41, v125
	v_mul_f32_e32 v233, v39, v127
	v_mul_f32_e32 v234, v37, v129
	v_mul_f32_e32 v235, v35, v131
	v_fmac_f32_e32 v228, v28, v116
	v_fmac_f32_e32 v229, v26, v118
	v_fmac_f32_e32 v230, v32, v120
	v_fmac_f32_e32 v231, v30, v122
	v_fmac_f32_e32 v232, v40, v124
	v_fmac_f32_e32 v233, v38, v126
	v_fmac_f32_e32 v234, v36, v128
	v_fmac_f32_e32 v235, v34, v130
	v_add_f32_e32 v228, v228, v229
	v_add_f32_e32 v230, v230, v231
	v_add_f32_e32 v232, v232, v233
	v_add_f32_e32 v234, v234, v235
	v_add_f32_e32 v87, 0, v228
	v_add_f32_e32 v87, v87, v230
	v_add_f32_e32 v87, v87, v232
	v_add_f32_e32 v87, v87, v234
	ds_read_b128 v[116:119], v56 offset:40960
	ds_read_b128 v[120:123], v56 offset:41984
	ds_read_b128 v[124:127], v56 offset:43008
	ds_read_b128 v[128:131], v56 offset:44032
	s_waitcnt lgkmcnt(8)
	v_mul_f32_e32 v228, v29, v133
	v_mul_f32_e32 v229, v27, v135
	v_mul_f32_e32 v230, v33, v137
	v_mul_f32_e32 v231, v31, v139
	v_mul_f32_e32 v232, v41, v141
	v_mul_f32_e32 v233, v39, v143
	v_mul_f32_e32 v234, v37, v145
	v_mul_f32_e32 v235, v35, v147
	v_fmac_f32_e32 v228, v28, v132
	v_fmac_f32_e32 v229, v26, v134
	v_fmac_f32_e32 v230, v32, v136
	v_fmac_f32_e32 v231, v30, v138
	v_fmac_f32_e32 v232, v40, v140
	v_fmac_f32_e32 v233, v38, v142
	v_fmac_f32_e32 v234, v36, v144
	v_fmac_f32_e32 v235, v34, v146
	v_add_f32_e32 v228, v228, v229
	v_add_f32_e32 v230, v230, v231
	v_add_f32_e32 v232, v232, v233
	v_add_f32_e32 v234, v234, v235
	v_add_f32_e32 v88, 0, v228
	v_add_f32_e32 v88, v88, v230
	v_add_f32_e32 v88, v88, v232
	v_add_f32_e32 v88, v88, v234
	ds_read_b128 v[132:135], v56 offset:45056
	ds_read_b128 v[136:139], v56 offset:46080
	ds_read_b128 v[140:143], v56 offset:47104
	ds_read_b128 v[144:147], v56 offset:48128
	s_waitcnt lgkmcnt(8)
	v_mul_f32_e32 v228, v29, v101
	v_mul_f32_e32 v229, v27, v103
	v_mul_f32_e32 v230, v33, v105
	v_mul_f32_e32 v231, v31, v107
	v_mul_f32_e32 v232, v41, v109
	v_mul_f32_e32 v233, v39, v111
	v_mul_f32_e32 v234, v37, v113
	v_mul_f32_e32 v235, v35, v115
	v_fmac_f32_e32 v228, v28, v100
	v_fmac_f32_e32 v229, v26, v102
	v_fmac_f32_e32 v230, v32, v104
	v_fmac_f32_e32 v231, v30, v106
	v_fmac_f32_e32 v232, v40, v108
	v_fmac_f32_e32 v233, v38, v110
	v_fmac_f32_e32 v234, v36, v112
	v_fmac_f32_e32 v235, v34, v114
	v_add_f32_e32 v228, v228, v229
	v_add_f32_e32 v230, v230, v231
	v_add_f32_e32 v232, v232, v233
	v_add_f32_e32 v234, v234, v235
	v_add_f32_e32 v89, 0, v228
	v_add_f32_e32 v89, v89, v230
	v_add_f32_e32 v89, v89, v232
	v_add_f32_e32 v89, v89, v234
	ds_read_b128 v[100:103], v56 offset:49152
	ds_read_b128 v[104:107], v56 offset:50176
	ds_read_b128 v[108:111], v56 offset:51200
	ds_read_b128 v[112:115], v56 offset:52224
	s_waitcnt lgkmcnt(8)
	v_mul_f32_e32 v228, v29, v117
	v_mul_f32_e32 v229, v27, v119
	v_mul_f32_e32 v230, v33, v121
	v_mul_f32_e32 v231, v31, v123
	v_mul_f32_e32 v232, v41, v125
	v_mul_f32_e32 v233, v39, v127
	v_mul_f32_e32 v234, v37, v129
	v_mul_f32_e32 v235, v35, v131
	v_fmac_f32_e32 v228, v28, v116
	v_fmac_f32_e32 v229, v26, v118
	v_fmac_f32_e32 v230, v32, v120
	v_fmac_f32_e32 v231, v30, v122
	v_fmac_f32_e32 v232, v40, v124
	v_fmac_f32_e32 v233, v38, v126
	v_fmac_f32_e32 v234, v36, v128
	v_fmac_f32_e32 v235, v34, v130
	v_add_f32_e32 v228, v228, v229
	v_add_f32_e32 v230, v230, v231
	v_add_f32_e32 v232, v232, v233
	v_add_f32_e32 v234, v234, v235
	v_add_f32_e32 v90, 0, v228
	v_add_f32_e32 v90, v90, v230
	v_add_f32_e32 v90, v90, v232
	v_add_f32_e32 v90, v90, v234
	ds_read_b128 v[116:119], v56 offset:53248
	ds_read_b128 v[120:123], v56 offset:54272
	ds_read_b128 v[124:127], v56 offset:55296
	ds_read_b128 v[128:131], v56 offset:56320
	s_waitcnt lgkmcnt(8)
	v_mul_f32_e32 v228, v29, v133
	v_mul_f32_e32 v229, v27, v135
	v_mul_f32_e32 v230, v33, v137
	v_mul_f32_e32 v231, v31, v139
	v_mul_f32_e32 v232, v41, v141
	v_mul_f32_e32 v233, v39, v143
	v_mul_f32_e32 v234, v37, v145
	v_mul_f32_e32 v235, v35, v147
	v_fmac_f32_e32 v228, v28, v132
	v_fmac_f32_e32 v229, v26, v134
	v_fmac_f32_e32 v230, v32, v136
	v_fmac_f32_e32 v231, v30, v138
	v_fmac_f32_e32 v232, v40, v140
	v_fmac_f32_e32 v233, v38, v142
	v_fmac_f32_e32 v234, v36, v144
	v_fmac_f32_e32 v235, v34, v146
	v_add_f32_e32 v228, v228, v229
	v_add_f32_e32 v230, v230, v231
	v_add_f32_e32 v232, v232, v233
	v_add_f32_e32 v234, v234, v235
	v_add_f32_e32 v91, 0, v228
	v_add_f32_e32 v91, v91, v230
	v_add_f32_e32 v91, v91, v232
	v_add_f32_e32 v91, v91, v234
	ds_read_b128 v[132:135], v56 offset:57344
	ds_read_b128 v[136:139], v56 offset:58368
	ds_read_b128 v[140:143], v56 offset:59392
	ds_read_b128 v[144:147], v56 offset:60416
	s_waitcnt lgkmcnt(8)
	v_mul_f32_e32 v228, v29, v101
	v_mul_f32_e32 v229, v27, v103
	v_mul_f32_e32 v230, v33, v105
	v_mul_f32_e32 v231, v31, v107
	v_mul_f32_e32 v232, v41, v109
	v_mul_f32_e32 v233, v39, v111
	v_mul_f32_e32 v234, v37, v113
	v_mul_f32_e32 v235, v35, v115
	v_fmac_f32_e32 v228, v28, v100
	v_fmac_f32_e32 v229, v26, v102
	v_fmac_f32_e32 v230, v32, v104
	v_fmac_f32_e32 v231, v30, v106
	v_fmac_f32_e32 v232, v40, v108
	v_fmac_f32_e32 v233, v38, v110
	v_fmac_f32_e32 v234, v36, v112
	v_fmac_f32_e32 v235, v34, v114
	v_add_f32_e32 v228, v228, v229
	v_add_f32_e32 v230, v230, v231
	v_add_f32_e32 v232, v232, v233
	v_add_f32_e32 v234, v234, v235
	v_add_f32_e32 v92, 0, v228
	v_add_f32_e32 v92, v92, v230
	v_add_f32_e32 v92, v92, v232
	v_add_f32_e32 v92, v92, v234
	ds_read_b128 v[100:103], v56 offset:61440
	ds_read_b128 v[104:107], v56 offset:62464
	ds_read_b128 v[108:111], v56 offset:63488
	ds_read_b128 v[112:115], v56 offset:64512
	s_waitcnt lgkmcnt(8)
	v_mul_f32_e32 v228, v29, v117
	v_mul_f32_e32 v229, v27, v119
	v_mul_f32_e32 v230, v33, v121
	v_mul_f32_e32 v231, v31, v123
	v_mul_f32_e32 v232, v41, v125
	v_mul_f32_e32 v233, v39, v127
	v_mul_f32_e32 v234, v37, v129
	v_mul_f32_e32 v235, v35, v131
	v_fmac_f32_e32 v228, v28, v116
	v_fmac_f32_e32 v229, v26, v118
	v_fmac_f32_e32 v230, v32, v120
	v_fmac_f32_e32 v231, v30, v122
	v_fmac_f32_e32 v232, v40, v124
	v_fmac_f32_e32 v233, v38, v126
	v_fmac_f32_e32 v234, v36, v128
	v_fmac_f32_e32 v235, v34, v130
	v_add_f32_e32 v228, v228, v229
	v_add_f32_e32 v230, v230, v231
	v_add_f32_e32 v232, v232, v233
	v_add_f32_e32 v234, v234, v235
	v_add_f32_e32 v93, 0, v228
	v_add_f32_e32 v93, v93, v230
	v_add_f32_e32 v93, v93, v232
	v_add_f32_e32 v93, v93, v234
	s_waitcnt lgkmcnt(4)
	v_mul_f32_e32 v228, v29, v133
	v_mul_f32_e32 v229, v27, v135
	v_mul_f32_e32 v230, v33, v137
	v_mul_f32_e32 v231, v31, v139
	v_mul_f32_e32 v232, v41, v141
	v_mul_f32_e32 v233, v39, v143
	v_mul_f32_e32 v234, v37, v145
	v_mul_f32_e32 v235, v35, v147
	v_fmac_f32_e32 v228, v28, v132
	v_fmac_f32_e32 v229, v26, v134
	v_fmac_f32_e32 v230, v32, v136
	v_fmac_f32_e32 v231, v30, v138
	v_fmac_f32_e32 v232, v40, v140
	v_fmac_f32_e32 v233, v38, v142
	v_fmac_f32_e32 v234, v36, v144
	v_fmac_f32_e32 v235, v34, v146
	v_add_f32_e32 v228, v228, v229
	v_add_f32_e32 v230, v230, v231
	v_add_f32_e32 v232, v232, v233
	v_add_f32_e32 v234, v234, v235
	v_add_f32_e32 v94, 0, v228
	v_add_f32_e32 v94, v94, v230
	v_add_f32_e32 v94, v94, v232
	v_add_f32_e32 v94, v94, v234
	s_waitcnt lgkmcnt(0)
	v_mul_f32_e32 v228, v29, v101
	v_mul_f32_e32 v229, v27, v103
	v_mul_f32_e32 v230, v33, v105
	v_mul_f32_e32 v231, v31, v107
	v_mul_f32_e32 v232, v41, v109
	v_mul_f32_e32 v233, v39, v111
	v_mul_f32_e32 v234, v37, v113
	v_mul_f32_e32 v235, v35, v115
	v_fmac_f32_e32 v228, v28, v100
	v_fmac_f32_e32 v229, v26, v102
	v_fmac_f32_e32 v230, v32, v104
	v_fmac_f32_e32 v231, v30, v106
	v_fmac_f32_e32 v232, v40, v108
	v_fmac_f32_e32 v233, v38, v110
	v_fmac_f32_e32 v234, v36, v112
	v_fmac_f32_e32 v235, v34, v114
	v_add_f32_e32 v228, v228, v229
	v_add_f32_e32 v230, v230, v231
	v_add_f32_e32 v232, v232, v233
	v_add_f32_e32 v234, v234, v235
	v_add_f32_e32 v95, 0, v228
	v_add_f32_e32 v95, v95, v230
	v_add_f32_e32 v95, v95, v232
	v_add_f32_e32 v95, v95, v234
	v_permlane32_swap_b32_e32 v80, v88
	v_permlane32_swap_b32_e32 v81, v89
	v_permlane32_swap_b32_e32 v82, v90
	v_permlane32_swap_b32_e32 v83, v91
	v_permlane32_swap_b32_e32 v84, v92
	v_permlane32_swap_b32_e32 v85, v93
	v_permlane32_swap_b32_e32 v86, v94
	v_permlane32_swap_b32_e32 v87, v95
	v_add_f32_e32 v80, v80, v88
	v_add_f32_e32 v81, v81, v89
	v_add_f32_e32 v82, v82, v90
	v_add_f32_e32 v83, v83, v91
	v_add_f32_e32 v84, v84, v92
	v_add_f32_e32 v85, v85, v93
	v_add_f32_e32 v86, v86, v94
	v_add_f32_e32 v87, v87, v95
	s_mov_b32 vcc_lo, 0xffff0000
	s_mov_b32 vcc_hi, 0xffff0000
	v_cndmask_b32_e32 v240, v84, v80, vcc
	v_cndmask_b32_e32 v241, v85, v81, vcc
	v_cndmask_b32_e32 v242, v86, v82, vcc
	v_cndmask_b32_e32 v243, v87, v83, vcc
	v_cndmask_b32_e32 v236, v80, v84, vcc
	v_cndmask_b32_e32 v237, v81, v85, vcc
	v_cndmask_b32_e32 v238, v82, v86, vcc
	v_cndmask_b32_e32 v239, v83, v87, vcc
	ds_swizzle_b32 v232, v240 offset:swizzle(SWAP,16)
	ds_swizzle_b32 v233, v241 offset:swizzle(SWAP,16)
	ds_swizzle_b32 v234, v242 offset:swizzle(SWAP,16)
	ds_swizzle_b32 v235, v243 offset:swizzle(SWAP,16)
	s_waitcnt lgkmcnt(0)
	v_add_f32_e32 v88, v236, v232
	v_add_f32_e32 v89, v237, v233
	v_add_f32_e32 v90, v238, v234
	v_add_f32_e32 v91, v239, v235
	v_add_f32_dpp v88, v88, v88 row_ror:8 row_mask:0xf bank_mask:0xf
	v_add_f32_dpp v89, v89, v89 row_ror:8 row_mask:0xf bank_mask:0xf
	v_add_f32_dpp v90, v90, v90 row_ror:8 row_mask:0xf bank_mask:0xf
	v_add_f32_dpp v91, v91, v91 row_ror:8 row_mask:0xf bank_mask:0xf
	v_add_f32_dpp v88, v88, v88 row_ror:4 row_mask:0xf bank_mask:0xf
	v_add_f32_dpp v89, v89, v89 row_ror:4 row_mask:0xf bank_mask:0xf
	v_add_f32_dpp v90, v90, v90 row_ror:4 row_mask:0xf bank_mask:0xf
	v_add_f32_dpp v91, v91, v91 row_ror:4 row_mask:0xf bank_mask:0xf
	v_add_f32_dpp v88, v88, v88 quad_perm:[2,3,0,1] row_mask:0xf bank_mask:0xf
	v_add_f32_dpp v89, v89, v89 quad_perm:[2,3,0,1] row_mask:0xf bank_mask:0xf
	v_add_f32_dpp v90, v90, v90 quad_perm:[2,3,0,1] row_mask:0xf bank_mask:0xf
	v_add_f32_dpp v91, v91, v91 quad_perm:[2,3,0,1] row_mask:0xf bank_mask:0xf
	v_add_f32_dpp v88, v88, v88 quad_perm:[1,0,3,2] row_mask:0xf bank_mask:0xf
	v_add_f32_dpp v89, v89, v89 quad_perm:[1,0,3,2] row_mask:0xf bank_mask:0xf
	v_add_f32_dpp v90, v90, v90 quad_perm:[1,0,3,2] row_mask:0xf bank_mask:0xf
	v_add_f32_dpp v91, v91, v91 quad_perm:[1,0,3,2] row_mask:0xf bank_mask:0xf
	s_mov_b32 vcc_lo, 0xaaaaaaaa
	s_mov_b32 vcc_hi, 0xaaaaaaaa
	v_cndmask_b32_e32 v92, v88, v89, vcc
	v_cndmask_b32_e32 v93, v90, v91, vcc
	s_mov_b32 vcc_lo, 0xcccccccc
	s_mov_b32 vcc_hi, 0xcccccccc
	v_cndmask_b32_e32 v92, v92, v93, vcc
	ds_bpermute_b32 v26, v97, v92
	s_waitcnt lgkmcnt(0)
	s_and_saveexec_b64 s[0:1], s[4:5]
	s_cbranch_execz .LBB0_693
	global_load_dword v28, v[14:15], off
	s_mov_b32 s2, 0xbfb8aa3b
	s_waitcnt vmcnt(0)
	v_add_f32_e32 v26, v26, v28
	v_mul_f32_e64 v27, |v26|, s2
	v_exp_f32_e32 v27, v27
	v_min_f32_e32 v26, 0, v26
	v_add_f32_e32 v27, 1.0, v27
	v_log_f32_e32 v27, v27
	s_nop 0
	v_fmac_f32_e32 v26, 0xbf317218, v27
	global_store_dword v[16:17], v26, off
	s_branch .LBB0_693
